# 7.12 softmax rescale test without cross-half bpermute on hot path (latent attention loop)
# speedup vs baseline: 1.0075x; 1.0075x over previous
.LBB0_892:
	v_lshl_or_b32 v172, s12, 14, v159
	v_add_u32_e32 v2, v172, v158
	ds_read_b128 v[2:5], v2 offset:4096
	ds_read_b128 v[144:147], v157 offset:49152
	v_xor_b32_e32 v128, 0x80000000, v169
	v_mov_b32_e32 v129, v128
	v_mov_b32_e32 v130, v128
	v_mov_b32_e32 v131, v128
	v_mov_b32_e32 v132, v128
	v_mov_b32_e32 v133, v128
	v_mov_b32_e32 v134, v128
	v_mov_b32_e32 v135, v128
	v_mov_b32_e32 v136, v128
	v_mov_b32_e32 v137, v128
	v_mov_b32_e32 v138, v128
	v_mov_b32_e32 v139, v128
	v_mov_b32_e32 v140, v128
	v_mov_b32_e32 v141, v128
	v_mov_b32_e32 v142, v128
	v_mov_b32_e32 v143, v128
	s_waitcnt lgkmcnt(0)
	s_nop 0
	v_mfma_f32_32x32x16_f16 v[128:143], v[2:5], v[144:147], v[128:143]
	v_add_u32_e32 v2, v172, v160
	ds_read_b128 v[2:5], v2 offset:4096
	ds_read_b128 v[10:13], v157 offset:57344
	s_waitcnt lgkmcnt(0)
	v_mfma_f32_32x32x16_f16 v[128:143], v[2:5], v[10:13], v[128:143]
	v_max_f32_e32 v2, v81, v81
	v_max_f32_e32 v3, v80, v80
	v_max_f32_e32 v2, v3, v2
	v_max3_f32 v2, v2, v82, v83
	v_max3_f32 v2, v2, v84, v85
	v_max3_f32 v2, v2, v86, v87
	v_max3_f32 v2, v2, v88, v89
	v_max3_f32 v2, v2, v90, v91
	v_max3_f32 v2, v2, v92, v93
	v_max3_f32 v2, v2, v94, v95
	v_cmp_lt_f32_e32 vcc, s61, v2
	s_cbranch_vccz .LBB0_894
	ds_bpermute_b32 v3, v153, v2
	s_waitcnt lgkmcnt(0)
	v_max_f32_e32 v3, v3, v3
	v_max_f32_e32 v2, v2, v3
	v_max_f32_e32 v2, v2, v2
	v_max_f32_e32 v2, 0, v2
	v_exp_f32_e64 v4, -v2
	v_add_f32_e32 v169, v169, v2
	v_pk_add_f32 v[80:81], v[80:81], v[2:3] op_sel_hi:[1,0] neg_lo:[0,1] neg_hi:[0,1]
	v_pk_add_f32 v[82:83], v[82:83], v[2:3] op_sel_hi:[1,0] neg_lo:[0,1] neg_hi:[0,1]
	v_mul_f32_e32 v171, v171, v4
	v_pk_add_f32 v[84:85], v[84:85], v[2:3] op_sel_hi:[1,0] neg_lo:[0,1] neg_hi:[0,1]
	v_pk_add_f32 v[86:87], v[86:87], v[2:3] op_sel_hi:[1,0] neg_lo:[0,1] neg_hi:[0,1]
	v_pk_add_f32 v[88:89], v[88:89], v[2:3] op_sel_hi:[1,0] neg_lo:[0,1] neg_hi:[0,1]
	v_pk_add_f32 v[90:91], v[90:91], v[2:3] op_sel_hi:[1,0] neg_lo:[0,1] neg_hi:[0,1]
	v_pk_add_f32 v[92:93], v[92:93], v[2:3] op_sel_hi:[1,0] neg_lo:[0,1] neg_hi:[0,1]
	v_pk_add_f32 v[94:95], v[94:95], v[2:3] op_sel_hi:[1,0] neg_lo:[0,1] neg_hi:[0,1]
	v_sub_f32_e32 v143, v143, v2
	v_sub_f32_e32 v142, v142, v2
	v_sub_f32_e32 v141, v141, v2
	v_sub_f32_e32 v140, v140, v2
	v_sub_f32_e32 v139, v139, v2
	v_sub_f32_e32 v138, v138, v2
	v_sub_f32_e32 v137, v137, v2
	v_sub_f32_e32 v136, v136, v2
	v_sub_f32_e32 v135, v135, v2
	v_sub_f32_e32 v134, v134, v2
	v_sub_f32_e32 v133, v133, v2
	v_sub_f32_e32 v132, v132, v2
	v_sub_f32_e32 v131, v131, v2
	v_sub_f32_e32 v130, v130, v2
	v_sub_f32_e32 v129, v129, v2
	v_sub_f32_e32 v128, v128, v2
	v_pk_mul_f32 v[30:31], v[30:31], v[4:5] op_sel_hi:[1,0]
	v_pk_mul_f32 v[28:29], v[28:29], v[4:5] op_sel_hi:[1,0]
	v_pk_mul_f32 v[26:27], v[26:27], v[4:5] op_sel_hi:[1,0]
	v_pk_mul_f32 v[24:25], v[24:25], v[4:5] op_sel_hi:[1,0]
	v_pk_mul_f32 v[22:23], v[22:23], v[4:5] op_sel_hi:[1,0]
	v_pk_mul_f32 v[20:21], v[20:21], v[4:5] op_sel_hi:[1,0]
	v_pk_mul_f32 v[18:19], v[18:19], v[4:5] op_sel_hi:[1,0]
	v_pk_mul_f32 v[16:17], v[16:17], v[4:5] op_sel_hi:[1,0]
	v_pk_mul_f32 v[46:47], v[46:47], v[4:5] op_sel_hi:[1,0]
	v_pk_mul_f32 v[44:45], v[44:45], v[4:5] op_sel_hi:[1,0]
	v_pk_mul_f32 v[42:43], v[42:43], v[4:5] op_sel_hi:[1,0]
	v_pk_mul_f32 v[40:41], v[40:41], v[4:5] op_sel_hi:[1,0]
	v_pk_mul_f32 v[38:39], v[38:39], v[4:5] op_sel_hi:[1,0]
	v_pk_mul_f32 v[36:37], v[36:37], v[4:5] op_sel_hi:[1,0]
	v_pk_mul_f32 v[34:35], v[34:35], v[4:5] op_sel_hi:[1,0]
	v_pk_mul_f32 v[32:33], v[32:33], v[4:5] op_sel_hi:[1,0]
.LBB0_894:
	v_exp_f32_e32 v173, v80
	v_add_u32_e32 v80, v172, v161
	ds_read2st64_b64 v[112:115], v80 offset0:16 offset1:24
	v_add_u32_e32 v80, v172, v162
	v_exp_f32_e32 v177, v84
	v_exp_f32_e32 v178, v85
	v_exp_f32_e32 v179, v86
	v_exp_f32_e32 v180, v87
	ds_read2st64_b64 v[84:87], v80 offset0:16 offset1:24
	v_exp_f32_e32 v174, v81
	v_exp_f32_e32 v175, v82
	v_exp_f32_e32 v176, v83
	v_exp_f32_e32 v185, v92
	v_exp_f32_e32 v186, v93
	v_exp_f32_e32 v187, v94
	v_exp_f32_e32 v188, v95
	s_waitcnt lgkmcnt(0)
	v_mov_b32_e32 v92, v112
	v_mov_b32_e32 v93, v113
	v_mov_b32_e32 v94, v84
	v_mov_b32_e32 v95, v85
	v_mov_b32_e32 v84, v114
	v_mov_b32_e32 v85, v115
	v_add_u32_e32 v80, v172, v163
	ds_read2st64_b64 v[116:119], v80 offset0:16 offset1:24
	v_add_u32_e32 v80, v172, v164
	ds_read2st64_b64 v[80:83], v80 offset0:16 offset1:24
	v_cvt_pkrtz_f16_f32 v2, v173, v174
	v_cvt_pkrtz_f16_f32 v3, v175, v176
	v_cvt_pkrtz_f16_f32 v4, v177, v178
	v_cvt_pkrtz_f16_f32 v5, v179, v180
	v_exp_f32_e32 v181, v88
	v_exp_f32_e32 v182, v89
	v_mfma_f32_32x32x16_f16 v[16:31], v[92:95], v[2:5], v[16:31]
	v_exp_f32_e32 v183, v90
	v_exp_f32_e32 v184, v91
	s_waitcnt lgkmcnt(0)
	v_mov_b32_e32 v88, v116
	v_mov_b32_e32 v89, v117
	v_mov_b32_e32 v90, v80
	v_mov_b32_e32 v91, v81
	v_mov_b32_e32 v80, v118
	v_mfma_f32_32x32x16_f16 v[32:47], v[84:87], v[2:5], v[32:47]
	v_mov_b32_e32 v81, v119
	v_cvt_pkrtz_f16_f32 v6, v181, v182
	v_cvt_pkrtz_f16_f32 v7, v183, v184
	v_cvt_pkrtz_f16_f32 v8, v185, v186
	v_cvt_pkrtz_f16_f32 v9, v187, v188
	v_add_u32_e32 v2, v172, v156
	v_xor_b32_e32 v112, 0x80000000, v168
	v_mfma_f32_32x32x16_f16 v[16:31], v[88:91], v[6:9], v[16:31]
	v_mov_b32_e32 v113, v112
	v_mov_b32_e32 v114, v112
	v_mov_b32_e32 v115, v112
	v_mov_b32_e32 v116, v112
	v_mov_b32_e32 v117, v112
	v_mov_b32_e32 v118, v112
	v_mov_b32_e32 v119, v112
	v_mfma_f32_32x32x16_f16 v[32:47], v[80:83], v[6:9], v[32:47]
	ds_read_b128 v[2:5], v2 offset:4096
	ds_read_b128 v[6:9], v154 offset:16384
	v_mov_b32_e32 v120, v112
	v_mov_b32_e32 v121, v112
	v_mov_b32_e32 v122, v112
	v_mov_b32_e32 v123, v112
	v_mov_b32_e32 v124, v112
	v_mov_b32_e32 v125, v112
	v_mov_b32_e32 v126, v112
	v_mov_b32_e32 v127, v112
	v_max_f32_e32 v189, v97, v97
	s_waitcnt lgkmcnt(0)
	v_mfma_f32_32x32x16_f16 v[112:127], v[2:5], v[6:9], v[112:127]
	v_add_u32_e32 v2, v172, v155
	ds_read_b128 v[190:193], v2 offset:4096
	ds_read_b128 v[2:5], v154 offset:24576
	s_waitcnt lgkmcnt(0)
	v_mfma_f32_32x32x16_f16 v[112:127], v[190:193], v[2:5], v[112:127]
	v_max_f32_e32 v190, v96, v96
	v_max_f32_e32 v189, v190, v189
	v_max3_f32 v189, v189, v98, v99
	v_max3_f32 v189, v189, v100, v101
	v_max3_f32 v189, v189, v102, v103
	v_max3_f32 v189, v189, v104, v105
	v_max3_f32 v189, v189, v106, v107
	v_max3_f32 v189, v189, v108, v109
	v_max3_f32 v189, v189, v110, v111
	v_cmp_lt_f32_e32 vcc, s61, v189
	s_cbranch_vccz .LBB0_896
	ds_bpermute_b32 v190, v153, v189
	s_waitcnt lgkmcnt(0)
	v_max_f32_e32 v190, v190, v190
	v_max_f32_e32 v189, v189, v190
	v_max_f32_e32 v189, v189, v189
	v_max_f32_e32 v190, 0, v189
	v_exp_f32_e64 v192, -v190
	v_add_f32_e32 v168, v168, v190
	v_pk_add_f32 v[96:97], v[96:97], v[190:191] op_sel_hi:[1,0] neg_lo:[0,1] neg_hi:[0,1]
	v_pk_add_f32 v[98:99], v[98:99], v[190:191] op_sel_hi:[1,0] neg_lo:[0,1] neg_hi:[0,1]
	v_mul_f32_e32 v170, v170, v192
	v_pk_add_f32 v[100:101], v[100:101], v[190:191] op_sel_hi:[1,0] neg_lo:[0,1] neg_hi:[0,1]
	v_pk_add_f32 v[102:103], v[102:103], v[190:191] op_sel_hi:[1,0] neg_lo:[0,1] neg_hi:[0,1]
	v_pk_add_f32 v[104:105], v[104:105], v[190:191] op_sel_hi:[1,0] neg_lo:[0,1] neg_hi:[0,1]
	v_pk_add_f32 v[106:107], v[106:107], v[190:191] op_sel_hi:[1,0] neg_lo:[0,1] neg_hi:[0,1]
	v_pk_add_f32 v[108:109], v[108:109], v[190:191] op_sel_hi:[1,0] neg_lo:[0,1] neg_hi:[0,1]
	v_pk_add_f32 v[110:111], v[110:111], v[190:191] op_sel_hi:[1,0] neg_lo:[0,1] neg_hi:[0,1]
	v_sub_f32_e32 v127, v127, v190
	v_sub_f32_e32 v126, v126, v190
	v_sub_f32_e32 v125, v125, v190
	v_sub_f32_e32 v124, v124, v190
	v_sub_f32_e32 v123, v123, v190
	v_sub_f32_e32 v122, v122, v190
	v_sub_f32_e32 v121, v121, v190
	v_sub_f32_e32 v120, v120, v190
	v_sub_f32_e32 v119, v119, v190
	v_sub_f32_e32 v118, v118, v190
	v_sub_f32_e32 v117, v117, v190
	v_sub_f32_e32 v116, v116, v190
	v_sub_f32_e32 v115, v115, v190
	v_sub_f32_e32 v114, v114, v190
	v_sub_f32_e32 v113, v113, v190
	v_sub_f32_e32 v112, v112, v190
	v_pk_mul_f32 v[62:63], v[62:63], v[192:193] op_sel_hi:[1,0]
	v_pk_mul_f32 v[60:61], v[60:61], v[192:193] op_sel_hi:[1,0]
	v_pk_mul_f32 v[58:59], v[58:59], v[192:193] op_sel_hi:[1,0]
	v_pk_mul_f32 v[56:57], v[56:57], v[192:193] op_sel_hi:[1,0]
	v_pk_mul_f32 v[54:55], v[54:55], v[192:193] op_sel_hi:[1,0]
	v_pk_mul_f32 v[52:53], v[52:53], v[192:193] op_sel_hi:[1,0]
	v_pk_mul_f32 v[50:51], v[50:51], v[192:193] op_sel_hi:[1,0]
	v_pk_mul_f32 v[48:49], v[48:49], v[192:193] op_sel_hi:[1,0]
	v_pk_mul_f32 v[78:79], v[78:79], v[192:193] op_sel_hi:[1,0]
	v_pk_mul_f32 v[76:77], v[76:77], v[192:193] op_sel_hi:[1,0]
	v_pk_mul_f32 v[74:75], v[74:75], v[192:193] op_sel_hi:[1,0]
	v_pk_mul_f32 v[72:73], v[72:73], v[192:193] op_sel_hi:[1,0]
	v_pk_mul_f32 v[70:71], v[70:71], v[192:193] op_sel_hi:[1,0]
	v_pk_mul_f32 v[68:69], v[68:69], v[192:193] op_sel_hi:[1,0]
	v_pk_mul_f32 v[66:67], v[66:67], v[192:193] op_sel_hi:[1,0]
	v_pk_mul_f32 v[64:65], v[64:65], v[192:193] op_sel_hi:[1,0]
.LBB0_896:
	v_add_f32_e32 v173, 0, v173
	v_add_f32_e32 v173, v174, v173
	v_add_f32_e32 v173, v175, v173
	v_add_f32_e32 v173, v176, v173
	v_add_f32_e32 v173, v177, v173
	v_add_f32_e32 v173, v178, v173
	v_add_f32_e32 v173, v179, v173
	v_add_f32_e32 v173, v180, v173
	v_add_f32_e32 v173, v181, v173
	v_add_f32_e32 v173, v182, v173
	v_add_f32_e32 v173, v183, v173
	v_add_f32_e32 v173, v184, v173
	v_add_f32_e32 v173, v185, v173
	v_exp_f32_e32 v96, v96
	v_exp_f32_e32 v97, v97
	v_exp_f32_e32 v98, v98
	v_exp_f32_e32 v99, v99
	v_exp_f32_e32 v100, v100
	v_exp_f32_e32 v101, v101
	v_exp_f32_e32 v102, v102
	v_exp_f32_e32 v103, v103
	v_add_f32_e32 v173, v186, v173
	v_add_f32_e32 v173, v187, v173
	v_add_f32_e32 v173, v188, v173
	v_add_f32_e32 v171, v171, v173
	v_add_u32_e32 v173, s11, v159
	v_cvt_pkrtz_f16_f32 v174, v96, v97
	v_cvt_pkrtz_f16_f32 v175, v98, v99
	v_cvt_pkrtz_f16_f32 v176, v100, v101
	v_cvt_pkrtz_f16_f32 v177, v102, v103
	v_exp_f32_e32 v104, v104
	v_exp_f32_e32 v105, v105
	v_mfma_f32_32x32x16_f16 v[48:63], v[92:95], v[174:177], v[48:63]
	v_exp_f32_e32 v106, v106
	v_exp_f32_e32 v107, v107
	v_exp_f32_e32 v108, v108
	v_exp_f32_e32 v109, v109
	v_exp_f32_e32 v110, v110
	v_exp_f32_e32 v111, v111
	v_cvt_pkrtz_f16_f32 v178, v104, v105
	v_mfma_f32_32x32x16_f16 v[64:79], v[84:87], v[174:177], v[64:79]
	v_add_u32_e32 v174, v173, v158
	ds_read_b128 v[174:177], v174
	v_cvt_pkrtz_f16_f32 v179, v106, v107
	v_cvt_pkrtz_f16_f32 v180, v108, v109
	v_cvt_pkrtz_f16_f32 v181, v110, v111
	s_nop 1
	v_mfma_f32_32x32x16_f16 v[64:79], v[80:83], v[178:181], v[64:79]
	v_xor_b32_e32 v80, 0x80000000, v169
	v_mov_b32_e32 v81, v80
	v_mov_b32_e32 v82, v80
	v_mov_b32_e32 v83, v80
	v_mov_b32_e32 v84, v80
	v_mov_b32_e32 v85, v80
	v_mov_b32_e32 v86, v80
	v_mfma_f32_32x32x16_f16 v[48:63], v[88:91], v[178:181], v[48:63]
	v_add_u32_e32 v178, v173, v160
	v_mov_b32_e32 v87, v80
	v_mov_b32_e32 v88, v80
	v_mov_b32_e32 v89, v80
	v_mov_b32_e32 v90, v80
	v_mov_b32_e32 v91, v80
	v_mov_b32_e32 v92, v80
	v_mov_b32_e32 v93, v80
	v_mov_b32_e32 v94, v80
	v_mov_b32_e32 v95, v80
	s_waitcnt lgkmcnt(0)
	s_nop 0
	v_mfma_f32_32x32x16_f16 v[80:95], v[174:177], v[144:147], v[80:95]
	ds_read_b128 v[144:147], v178
	s_waitcnt lgkmcnt(0)
	v_mfma_f32_32x32x16_f16 v[80:95], v[144:147], v[10:13], v[80:95]
	v_max_f32_e32 v10, v129, v129
	v_max_f32_e32 v11, v128, v128
	v_max_f32_e32 v10, v11, v10
	v_max3_f32 v10, v10, v130, v131
	v_max3_f32 v10, v10, v132, v133
	v_max3_f32 v10, v10, v134, v135
	v_max3_f32 v10, v10, v136, v137
	v_max3_f32 v10, v10, v138, v139
	v_max3_f32 v10, v10, v140, v141
	v_max3_f32 v10, v10, v142, v143
	v_cmp_lt_f32_e32 vcc, s61, v10
	s_cbranch_vccz .LBB0_898
	ds_bpermute_b32 v11, v153, v10
	s_waitcnt lgkmcnt(0)
	v_max_f32_e32 v11, v11, v11
	v_max_f32_e32 v10, v10, v11
	v_max_f32_e32 v10, v10, v10
	v_max_f32_e32 v10, 0, v10
	v_exp_f32_e64 v12, -v10
	v_add_f32_e32 v169, v169, v10
	v_pk_add_f32 v[128:129], v[128:129], v[10:11] op_sel_hi:[1,0] neg_lo:[0,1] neg_hi:[0,1]
	v_pk_add_f32 v[130:131], v[130:131], v[10:11] op_sel_hi:[1,0] neg_lo:[0,1] neg_hi:[0,1]
	v_mul_f32_e32 v171, v171, v12
	v_pk_add_f32 v[132:133], v[132:133], v[10:11] op_sel_hi:[1,0] neg_lo:[0,1] neg_hi:[0,1]
	v_pk_add_f32 v[134:135], v[134:135], v[10:11] op_sel_hi:[1,0] neg_lo:[0,1] neg_hi:[0,1]
	v_pk_add_f32 v[136:137], v[136:137], v[10:11] op_sel_hi:[1,0] neg_lo:[0,1] neg_hi:[0,1]
	v_pk_add_f32 v[138:139], v[138:139], v[10:11] op_sel_hi:[1,0] neg_lo:[0,1] neg_hi:[0,1]
	v_pk_add_f32 v[140:141], v[140:141], v[10:11] op_sel_hi:[1,0] neg_lo:[0,1] neg_hi:[0,1]
	v_pk_add_f32 v[142:143], v[142:143], v[10:11] op_sel_hi:[1,0] neg_lo:[0,1] neg_hi:[0,1]
	v_sub_f32_e32 v95, v95, v10
	v_sub_f32_e32 v94, v94, v10
	v_sub_f32_e32 v93, v93, v10
	v_sub_f32_e32 v92, v92, v10
	v_sub_f32_e32 v91, v91, v10
	v_sub_f32_e32 v90, v90, v10
	v_sub_f32_e32 v89, v89, v10
	v_sub_f32_e32 v88, v88, v10
	v_sub_f32_e32 v87, v87, v10
	v_sub_f32_e32 v86, v86, v10
	v_sub_f32_e32 v85, v85, v10
	v_sub_f32_e32 v84, v84, v10
	v_sub_f32_e32 v83, v83, v10
	v_sub_f32_e32 v82, v82, v10
	v_sub_f32_e32 v81, v81, v10
	v_sub_f32_e32 v80, v80, v10
	v_pk_mul_f32 v[30:31], v[30:31], v[12:13] op_sel_hi:[1,0]
	v_pk_mul_f32 v[28:29], v[28:29], v[12:13] op_sel_hi:[1,0]
	v_pk_mul_f32 v[26:27], v[26:27], v[12:13] op_sel_hi:[1,0]
	v_pk_mul_f32 v[24:25], v[24:25], v[12:13] op_sel_hi:[1,0]
	v_pk_mul_f32 v[22:23], v[22:23], v[12:13] op_sel_hi:[1,0]
	v_pk_mul_f32 v[20:21], v[20:21], v[12:13] op_sel_hi:[1,0]
	v_pk_mul_f32 v[18:19], v[18:19], v[12:13] op_sel_hi:[1,0]
	v_pk_mul_f32 v[16:17], v[16:17], v[12:13] op_sel_hi:[1,0]
	v_pk_mul_f32 v[46:47], v[46:47], v[12:13] op_sel_hi:[1,0]
	v_pk_mul_f32 v[44:45], v[44:45], v[12:13] op_sel_hi:[1,0]
	v_pk_mul_f32 v[42:43], v[42:43], v[12:13] op_sel_hi:[1,0]
	v_pk_mul_f32 v[40:41], v[40:41], v[12:13] op_sel_hi:[1,0]
	v_pk_mul_f32 v[38:39], v[38:39], v[12:13] op_sel_hi:[1,0]
	v_pk_mul_f32 v[36:37], v[36:37], v[12:13] op_sel_hi:[1,0]
	v_pk_mul_f32 v[34:35], v[34:35], v[12:13] op_sel_hi:[1,0]
	v_pk_mul_f32 v[32:33], v[32:33], v[12:13] op_sel_hi:[1,0]
.LBB0_898:
	v_add_f32_e32 v10, 0, v96
	v_add_f32_e32 v10, v97, v10
	v_add_f32_e32 v10, v98, v10
	v_add_f32_e32 v10, v99, v10
	v_add_f32_e32 v10, v100, v10
	v_add_f32_e32 v10, v101, v10
	v_add_f32_e32 v10, v102, v10
	v_add_f32_e32 v10, v103, v10
	v_add_f32_e32 v10, v104, v10
	v_add_f32_e32 v10, v105, v10
	v_add_f32_e32 v10, v106, v10
	v_add_f32_e32 v10, v107, v10
	v_add_f32_e32 v10, v108, v10
	v_add_f32_e32 v10, v109, v10
	v_add_f32_e32 v10, v110, v10
	v_add_f32_e32 v10, v111, v10
	v_add_f32_e32 v144, v170, v10
	v_add_u32_e32 v10, v172, v166
	ds_read2st64_b64 v[104:107], v10 offset0:16 offset1:24
	v_add_u32_e32 v10, v172, v167
	v_exp_f32_e32 v145, v128
	v_exp_f32_e32 v146, v129
	v_exp_f32_e32 v147, v130
	v_exp_f32_e32 v170, v131
	ds_read2st64_b64 v[128:131], v10 offset0:16 offset1:24
	v_exp_f32_e32 v174, v132
	v_exp_f32_e32 v175, v133
	v_exp_f32_e32 v176, v134
	v_exp_f32_e32 v177, v135
	v_exp_f32_e32 v178, v136
	v_exp_f32_e32 v179, v137
	v_exp_f32_e32 v180, v138
	v_exp_f32_e32 v181, v139
	s_waitcnt lgkmcnt(0)
	v_mov_b32_e32 v136, v104
	v_mov_b32_e32 v137, v105
	v_mov_b32_e32 v138, v128
	v_mov_b32_e32 v139, v129
	v_mov_b32_e32 v128, v106
	v_mov_b32_e32 v129, v107
	v_add_u32_e32 v10, v172, v1
	ds_read2st64_b64 v[108:111], v10 offset0:16 offset1:24
	v_add_u32_e32 v10, v172, v165
	ds_read2st64_b64 v[10:13], v10 offset0:16 offset1:24
	v_cvt_pkrtz_f16_f32 v96, v145, v146
	v_cvt_pkrtz_f16_f32 v97, v147, v170
	v_cvt_pkrtz_f16_f32 v98, v174, v175
	v_cvt_pkrtz_f16_f32 v99, v176, v177
	v_add_u32_e32 v172, v173, v155
	v_add_u32_e32 v173, v173, v156
	v_mfma_f32_32x32x16_f16 v[16:31], v[136:139], v[96:99], v[16:31]
	ds_read_b128 v[182:185], v173
	v_exp_f32_e32 v140, v140
	v_exp_f32_e32 v141, v141
	v_exp_f32_e32 v142, v142
	v_exp_f32_e32 v143, v143
	s_waitcnt lgkmcnt(0)
	v_mov_b32_e32 v132, v108
	v_mov_b32_e32 v133, v109
	v_mfma_f32_32x32x16_f16 v[32:47], v[128:131], v[96:99], v[32:47]
	v_mov_b32_e32 v134, v10
	v_mov_b32_e32 v135, v11
	v_mov_b32_e32 v10, v110
	v_mov_b32_e32 v11, v111
	v_cvt_pkrtz_f16_f32 v100, v178, v179
	v_cvt_pkrtz_f16_f32 v101, v180, v181
	v_cvt_pkrtz_f16_f32 v102, v140, v141
	v_cvt_pkrtz_f16_f32 v103, v142, v143
	v_xor_b32_e32 v96, 0x80000000, v168
	v_mov_b32_e32 v97, v96
	v_mfma_f32_32x32x16_f16 v[16:31], v[132:135], v[100:103], v[16:31]
	v_mov_b32_e32 v98, v96
	v_mov_b32_e32 v99, v96
	v_mov_b32_e32 v104, v96
	v_mov_b32_e32 v105, v96
	v_mov_b32_e32 v106, v96
	v_mov_b32_e32 v107, v96
	v_mov_b32_e32 v108, v96
	v_mfma_f32_32x32x16_f16 v[32:47], v[10:13], v[100:103], v[32:47]
	v_mov_b32_e32 v100, v96
	v_mov_b32_e32 v101, v96
	v_mov_b32_e32 v102, v96
	v_mov_b32_e32 v103, v96
	v_mov_b32_e32 v109, v96
	v_mov_b32_e32 v110, v96
	v_mov_b32_e32 v111, v96
	s_nop 1
	v_mfma_f32_32x32x16_f16 v[96:111], v[182:185], v[6:9], v[96:111]
	ds_read_b128 v[6:9], v172
	s_waitcnt lgkmcnt(0)
	v_mfma_f32_32x32x16_f16 v[96:111], v[6:9], v[2:5], v[96:111]
	v_max_f32_e32 v2, v113, v113
	v_max_f32_e32 v3, v112, v112
	v_max_f32_e32 v2, v3, v2
	v_max3_f32 v2, v2, v114, v115
	v_max3_f32 v2, v2, v116, v117
	v_max3_f32 v2, v2, v118, v119
	v_max3_f32 v2, v2, v120, v121
	v_max3_f32 v2, v2, v122, v123
	v_max3_f32 v2, v2, v124, v125
	v_max3_f32 v2, v2, v126, v127
	v_cmp_lt_f32_e32 vcc, s61, v2
	s_cbranch_vccz .LBB0_900
	ds_bpermute_b32 v3, v153, v2
	s_waitcnt lgkmcnt(0)
	v_max_f32_e32 v3, v3, v3
	v_max_f32_e32 v2, v2, v3
	v_max_f32_e32 v2, v2, v2
	v_max_f32_e32 v2, 0, v2
	v_exp_f32_e64 v4, -v2
	v_add_f32_e32 v168, v168, v2
	v_pk_add_f32 v[112:113], v[112:113], v[2:3] op_sel_hi:[1,0] neg_lo:[0,1] neg_hi:[0,1]
	v_pk_add_f32 v[114:115], v[114:115], v[2:3] op_sel_hi:[1,0] neg_lo:[0,1] neg_hi:[0,1]
	v_mul_f32_e32 v144, v144, v4
	v_pk_add_f32 v[116:117], v[116:117], v[2:3] op_sel_hi:[1,0] neg_lo:[0,1] neg_hi:[0,1]
	v_pk_add_f32 v[118:119], v[118:119], v[2:3] op_sel_hi:[1,0] neg_lo:[0,1] neg_hi:[0,1]
	v_pk_add_f32 v[120:121], v[120:121], v[2:3] op_sel_hi:[1,0] neg_lo:[0,1] neg_hi:[0,1]
	v_pk_add_f32 v[122:123], v[122:123], v[2:3] op_sel_hi:[1,0] neg_lo:[0,1] neg_hi:[0,1]
	v_pk_add_f32 v[124:125], v[124:125], v[2:3] op_sel_hi:[1,0] neg_lo:[0,1] neg_hi:[0,1]
	v_pk_add_f32 v[126:127], v[126:127], v[2:3] op_sel_hi:[1,0] neg_lo:[0,1] neg_hi:[0,1]
	v_sub_f32_e32 v111, v111, v2
	v_sub_f32_e32 v110, v110, v2
	v_sub_f32_e32 v109, v109, v2
	v_sub_f32_e32 v108, v108, v2
	v_sub_f32_e32 v107, v107, v2
	v_sub_f32_e32 v106, v106, v2
	v_sub_f32_e32 v105, v105, v2
	v_sub_f32_e32 v104, v104, v2
	v_sub_f32_e32 v103, v103, v2
	v_sub_f32_e32 v102, v102, v2
	v_sub_f32_e32 v101, v101, v2
	v_sub_f32_e32 v100, v100, v2
	v_sub_f32_e32 v99, v99, v2
	v_sub_f32_e32 v98, v98, v2
	v_sub_f32_e32 v97, v97, v2
	v_sub_f32_e32 v96, v96, v2
	v_pk_mul_f32 v[62:63], v[62:63], v[4:5] op_sel_hi:[1,0]
	v_pk_mul_f32 v[60:61], v[60:61], v[4:5] op_sel_hi:[1,0]
	v_pk_mul_f32 v[58:59], v[58:59], v[4:5] op_sel_hi:[1,0]
	v_pk_mul_f32 v[56:57], v[56:57], v[4:5] op_sel_hi:[1,0]
	v_pk_mul_f32 v[54:55], v[54:55], v[4:5] op_sel_hi:[1,0]
	v_pk_mul_f32 v[52:53], v[52:53], v[4:5] op_sel_hi:[1,0]
	v_pk_mul_f32 v[50:51], v[50:51], v[4:5] op_sel_hi:[1,0]
	v_pk_mul_f32 v[48:49], v[48:49], v[4:5] op_sel_hi:[1,0]
	v_pk_mul_f32 v[78:79], v[78:79], v[4:5] op_sel_hi:[1,0]
	v_pk_mul_f32 v[76:77], v[76:77], v[4:5] op_sel_hi:[1,0]
	v_pk_mul_f32 v[74:75], v[74:75], v[4:5] op_sel_hi:[1,0]
	v_pk_mul_f32 v[72:73], v[72:73], v[4:5] op_sel_hi:[1,0]
	v_pk_mul_f32 v[70:71], v[70:71], v[4:5] op_sel_hi:[1,0]
	v_pk_mul_f32 v[68:69], v[68:69], v[4:5] op_sel_hi:[1,0]
	v_pk_mul_f32 v[66:67], v[66:67], v[4:5] op_sel_hi:[1,0]
	v_pk_mul_f32 v[64:65], v[64:65], v[4:5] op_sel_hi:[1,0]
